# P2 drain overlaps: scan's store drain behind the Y-GEMM prologue setup, Y-GEMM's drain behind the attention setup and entry prefetch
# speedup vs baseline: 1.0017x; 1.0011x over previous
; __device__ __forceinline__ unsigned cvt_pk_bf16(float lo, float hi) { unsigned r; asm volatile("v_cvt_pk_bf16_f32 %0, %1, %2" : "=v"(r) : "v"(lo), "v"(hi)); return r; }
; __global__ void __launch_bounds__(NWAVES * 64, 2) hymba_fwd(Args a) {
;     ...
;             unsigned* sp = (unsigned*)(A2 + row0 * A2LD + 256) + lane;
; #pragma unroll
;             for (int i = 0; i < 32; ++i) {
;                 sp[(size_t)i * (A2LD / 2)] = cvt_pk_bf16(sr, si);
;                 const float nr = lr * sr - li * si + zz[i].x, ni = lr * si + li * sr + zz[i].y; sr = nr; si = ni;
;             }
;         }
;         asm volatile("s_waitcnt vmcnt(0)" ::: "memory"); __syncthreads();
.LBB0_638:
	v_writelane_b32 v254, s87, 51
	v_writelane_b32 v254, s86, 52
	s_add_u32 s80, s94, 0x13000000
	s_mulk_i32 s1, 0x300
	s_mul_hi_u32 s8, s0, 0x300
	s_addc_u32 s81, s95, 0
	s_add_i32 s8, s8, s1
	s_mulk_i32 s0, 0x300
	v_readlane_b32 s10, v254, 45
	v_readlane_b32 s11, v254, 46
	s_add_u32 s0, s10, s0
	s_addc_u32 s1, s11, s8
	v_lshlrev_b32_e32 v6, 2, v130
	v_cvt_pk_bf16_f32 v3, v4, v5
	global_store_dword v6, v3, s[0:1] offset:512
	v_cvt_pk_bf16_f32 v3, v8, v9
	v_mov_b32_e32 v2, 0
	global_store_dword v6, v3, s[0:1] offset:1280
	v_cvt_pk_bf16_f32 v3, v12, v13
	v_mov_b32_e32 v7, v2
	global_store_dword v6, v3, s[0:1] offset:2048
	v_cvt_pk_bf16_f32 v3, v14, v15
	v_lshl_add_u64 v[10:11], s[0:1], 0, v[6:7]
	s_mov_b64 s[86:87], 0x200
	global_store_dword v6, v3, s[0:1] offset:2816
	v_cvt_pk_bf16_f32 v3, v16, v17
	global_store_dword v6, v3, s[0:1] offset:3584
	s_movk_i32 s0, 0x1000
	v_lshl_add_u64 v[18:19], v[10:11], 0, s[86:87]
	v_cvt_pk_bf16_f32 v3, v20, v21
	v_add_co_u32_e32 v4, vcc, s0, v10
	global_store_dword v[18:19], v3, off offset:3840
	v_cvt_pk_bf16_f32 v3, v26, v27
	s_nop 0
	v_addc_co_u32_e32 v5, vcc, 0, v11, vcc
	global_store_dword v[4:5], v3, off offset:1024
	v_cvt_pk_bf16_f32 v3, v30, v31
	global_store_dword v[4:5], v3, off offset:1792
	v_cvt_pk_bf16_f32 v3, v36, v37
	s_movk_i32 s0, 0x2000
	global_store_dword v[4:5], v3, off offset:2560
	v_cvt_pk_bf16_f32 v3, v40, v41
	global_store_dword v[4:5], v3, off offset:3328
	v_add_co_u32_e32 v4, vcc, s0, v10
	v_cvt_pk_bf16_f32 v3, v46, v47
	s_movk_i32 s0, 0x3000
	s_nop 0
	v_addc_co_u32_e32 v5, vcc, 0, v11, vcc
	global_store_dword v[4:5], v3, off
	v_cvt_pk_bf16_f32 v3, v48, v49
	global_store_dword v[4:5], v3, off offset:768
	v_cvt_pk_bf16_f32 v3, v54, v55
	global_store_dword v[4:5], v3, off offset:1536
	v_cvt_pk_bf16_f32 v3, v60, v61
	global_store_dword v[4:5], v3, off offset:2304
	v_cvt_pk_bf16_f32 v3, v62, v63
	global_store_dword v[4:5], v3, off offset:3072
	v_cvt_pk_bf16_f32 v3, v66, v67
	global_store_dword v[4:5], v3, off offset:3840
	v_add_co_u32_e32 v4, vcc, s0, v10
	v_cvt_pk_bf16_f32 v3, v76, v77
	s_movk_i32 s0, 0x4000
	s_nop 0
	v_addc_co_u32_e32 v5, vcc, 0, v11, vcc
	global_store_dword v[4:5], v3, off offset:512
	v_cvt_pk_bf16_f32 v3, v80, v81
	global_store_dword v[4:5], v3, off offset:1280
	v_cvt_pk_bf16_f32 v3, v86, v87
	global_store_dword v[4:5], v3, off offset:2048
	v_cvt_pk_bf16_f32 v3, v94, v95
	global_store_dword v[4:5], v3, off offset:2816
	v_cvt_pk_bf16_f32 v3, v98, v99
	global_store_dword v[4:5], v3, off offset:3584
	v_add_co_u32_e32 v4, vcc, s0, v10
	v_cvt_pk_bf16_f32 v3, v104, v105
	s_movk_i32 s0, 0x5000
	s_nop 0
	v_addc_co_u32_e32 v5, vcc, 0, v11, vcc
	global_store_dword v[4:5], v3, off offset:256
	v_cvt_pk_bf16_f32 v3, v106, v107
	global_store_dword v[4:5], v3, off offset:1024
	v_cvt_pk_bf16_f32 v3, v112, v113
	global_store_dword v[4:5], v3, off offset:1792
	v_cvt_pk_bf16_f32 v3, v114, v115
	global_store_dword v[4:5], v3, off offset:2560
	v_cvt_pk_bf16_f32 v3, v116, v117
	global_store_dword v[4:5], v3, off offset:3328
	v_add_co_u32_e32 v4, vcc, s0, v10
	v_cvt_pk_bf16_f32 v3, v118, v119
	v_readlane_b32 s8, v254, 49
	s_nop 0
	v_addc_co_u32_e32 v5, vcc, 0, v11, vcc
	global_store_dword v[4:5], v3, off
	v_cvt_pk_bf16_f32 v3, v120, v121
	global_store_dword v[4:5], v3, off offset:768
	v_cvt_pk_bf16_f32 v3, v122, v123
	global_store_dword v[4:5], v3, off offset:1536
	v_cvt_pk_bf16_f32 v3, v124, v125
	global_store_dword v[4:5], v3, off offset:2304
	v_cvt_pk_bf16_f32 v3, v126, v127
	global_store_dword v[4:5], v3, off offset:3072
	v_cvt_pk_bf16_f32 v3, v128, v129
	global_store_dword v[4:5], v3, off offset:3840
	v_mov_b32_e32 v3, v0
	v_readlane_b32 s9, v254, 50
	s_and_b64 vcc, exec, s[8:9]
	v_readfirstlane_b32 s0, v3
	s_cbranch_vccz .LBB0_654
; #define PG8_STAGE(bufoff, gbase, voff) do { _Pragma("unroll") for (int _i = 0; _i < 2; ++_i) \
;         __builtin_amdgcn_global_load_lds((const unsigned*)((const char*)(gbase) + (voff)[_i]), (PG8_LAS unsigned*)(lds + (bufoff) + ldsw + _i * 8192), 16, 0, 0); } while (0)
; #define PG8_WAIT_V(n) asm volatile("s_waitcnt vmcnt(" #n ")" ::: "memory")
; #define PG8_BAR __builtin_amdgcn_s_barrier()
; template <class Epi, class Sched, bool ALIGN_EPI>
; __device__ __forceinline__ void gemm_phase(PG8_LAS unsigned char* lds, const Gemm g, const Sched& S, const Epi& E) {
;     int tid_ = threadIdx.x; asm volatile("" : "+v"(tid_));
;     const int tid = tid_, wid = __builtin_amdgcn_readfirstlane(tid >> 6), lane = tid & 63, wr = wid >> 2, wc = wid & 3, fr = lane & 15, fq = lane >> 4;
;     const int nt = g.K / BK;
;     unsigned voffA[2], voffB[2];
; #pragma unroll
;     for (int i = 0; i < 2; ++i) { int R, C; stage_rc(tid * 16 + i * 8192, R, C); const int Rb = Epi::PERM ? ((R & ~31) + perm32(R & 31)) : R;
;         voffA[i] = g.ablk ? (unsigned)((C >> 4) * g.ablk + R * 16 + (C & 15)) * 2u : (unsigned)(R * g.lda + C) * 2u; voffB[i] = (unsigned)(Rb * g.ldb + C) * 2u; }
;     const size_t kstep = (size_t)(BK * 2), kstepA = g.ablk ? (size_t)4 * g.ablk * 2 : kstep;
;     const size_t hstepA = g.ablk ? (size_t)HALF * 16 * 2 : (size_t)HALF * g.lda * 2, hstepB = (size_t)HALF * g.ldb * 2;
;     const size_t tstepA = 2 * hstepA, tstepB = 2 * hstepB;
;     const unsigned ldsw = (unsigned)wid * 1024u;
;     const size_t tailoff = (size_t)(nt - 2) * (size_t)(BK * 2), tailoffA = (size_t)(nt - 2) * kstepA;
;     const int aoff = lds_byte(wr * 64 + fr, fq * 8), boff = lds_byte(wc * 32 + fr, fq * 8);
;     ...
;     const char* cA = (const char*)g.A + (size_t)cur.pm * tstepA; const char* cB = (const char*)g.Bt + (size_t)cur.pn * tstepB;
;     PG8_STAGE(PG8_SB(0, 0), cB, voffB); PG8_STAGE(PG8_SB(0, 1), cB + hstepB, voffB); PG8_STAGE(PG8_SA(0, 0), cA, voffA); PG8_STAGE(PG8_SA(0, 1), cA + hstepA, voffA);
;     if (wr == 1) PG8_BAR;
;     PG8_WAIT_V(2); PG8_BAR;
;     PG8_STAGE(PG8_SB(1, 0), cB + kstep, voffB); PG8_STAGE(PG8_SA(1, 0), cA + kstepA, voffA); PG8_STAGE(PG8_SB(1, 1), cB + hstepB + kstep, voffB);
;     PG8_WAIT_V(6); PG8_BAR;
	v_lshlrev_b32_e32 v4, 4, v3
	v_add_u32_e32 v5, 0x2000, v4
	v_ashrrev_i32_e32 v6, 31, v5
	v_lshrrev_b32_e32 v6, 22, v6
	v_add_u32_e32 v6, v5, v6
	v_ashrrev_i32_e32 v6, 10, v6
	v_mul_i32_i24_e32 v7, 0x400, v6
	v_sub_u32_e32 v5, v5, v7
	v_lshrrev_b32_e32 v7, 4, v5
	v_bitop3_b32 v5, v7, v5, 32 bitop3:0x6c
	v_ashrrev_i32_e32 v7, 31, v5
	v_lshrrev_b32_e32 v7, 26, v7
	v_add_u32_e32 v7, v5, v7
	v_lshlrev_b32_e32 v9, 3, v6
	v_ashrrev_i32_e32 v8, 6, v7
	v_and_b32_e32 v9, -16, v9
	v_add_u32_e32 v9, v8, v9
	v_and_b32_e32 v8, 3, v8
	s_mov_b32 s8, 0x1ffffe0
	v_lshrrev_b32_e32 v10, 2, v9
	v_lshlrev_b32_e32 v11, 1, v9
	v_and_b32_e32 v7, 0xc0, v7
	v_and_or_b32 v8, v9, s8, v8
	v_and_b32_e32 v10, 4, v10
	v_and_b32_e32 v11, 24, v11
	v_lshlrev_b32_e32 v6, 5, v6
	v_sub_u32_e32 v5, v5, v7
	v_mov_b32_e32 v7, 1
	v_or3_b32 v8, v8, v10, v11
	s_movk_i32 s9, 0x180
	v_and_b32_e32 v6, 32, v6
	v_ashrrev_i16_sdwa v5, v7, sext(v5) dst_sel:DWORD dst_unused:UNUSED_PAD src0_sel:DWORD src1_sel:BYTE_0
	v_mul_lo_u32 v8, v8, s9
	v_add_u32_sdwa v5, v6, sext(v5) dst_sel:DWORD dst_unused:UNUSED_PAD src0_sel:DWORD src1_sel:WORD_0
	v_mul_lo_u32 v6, v9, s9
	v_add_lshl_u32 v132, v8, v5, 1
	v_add_lshl_u32 v134, v5, v6, 1
	v_bfe_i32 v5, v3, 27, 1
	v_lshrrev_b32_e32 v5, 22, v5
	v_add_u32_e32 v5, v4, v5
	v_and_b32_e32 v5, 0xfffffc00, v5
	v_sub_u32_e32 v4, v4, v5
	v_lshrrev_b32_e32 v5, 4, v4
	v_ashrrev_i32_e32 v8, 31, v3
	v_bitop3_b32 v4, v5, v4, 32 bitop3:0x6c
	v_lshrrev_b32_e32 v8, 26, v8
	v_ashrrev_i32_e32 v5, 31, v4
	v_add_u32_e32 v8, v3, v8
	v_lshrrev_b32_e32 v5, 26, v5
	v_ashrrev_i32_e32 v8, 6, v8
	v_add_u32_e32 v5, v4, v5
	v_lshlrev_b32_e32 v9, 3, v8
	v_ashrrev_i32_e32 v6, 6, v5
	v_and_b32_e32 v9, -16, v9
	s_add_u32 s39, s94, 0x5800000
	v_add_u32_e32 v9, v6, v9
	v_and_b32_e32 v6, 3, v6
	s_addc_u32 s40, s95, 0
	s_ashr_i32 s10, s0, 6
	v_and_or_b32 v6, v9, s8, v6
	v_lshrrev_b32_e32 v10, 2, v9
	v_lshlrev_b32_e32 v11, 1, v9
	v_and_b32_e32 v5, 0xc0, v5
	s_mul_i32 s7, s7, 0x30000
	s_mul_hi_u32 s8, s6, 0x30000
	s_ashr_i32 s1, s0, 8
	s_lshl_b32 s41, s10, 10
	v_and_b32_e32 v10, 4, v10
	v_and_b32_e32 v11, 24, v11
	v_lshlrev_b32_e32 v8, 5, v8
	v_sub_u32_e32 v4, v4, v5
	s_add_i32 s8, s8, s7
	s_mul_i32 s7, s6, 0x30000
	v_or3_b32 v6, v6, v10, v11
	v_and_b32_e32 v8, 32, v8
	v_ashrrev_i16_sdwa v4, v7, sext(v4) dst_sel:DWORD dst_unused:UNUSED_PAD src0_sel:DWORD src1_sel:BYTE_0
	s_add_u32 s30, s39, s7
	v_mul_lo_u32 v6, v6, s9
	v_add_u32_sdwa v4, v8, sext(v4) dst_sel:DWORD dst_unused:UNUSED_PAD src0_sel:DWORD src1_sel:WORD_0
	s_addc_u32 s31, s40, s8
	s_add_i32 s42, s41, 0
	v_add_lshl_u32 v136, v6, v4, 1
	s_add_i32 m0, s42, 0x10000
	v_mul_lo_u32 v5, v9, s9
	s_waitcnt vmcnt(0)
	s_barrier
	global_load_lds_dwordx4 v136, s[30:31]
	s_add_i32 m0, s42, 0x12000
	s_add_u32 s8, s30, 0x18000
	global_load_lds_dwordx4 v132, s[30:31]
	s_addc_u32 s9, s31, 0
	s_add_i32 m0, s42, 0x14000
	v_add_lshl_u32 v138, v4, v5, 1
	global_load_lds_dwordx4 v136, s[8:9]
	s_add_i32 m0, s42, 0x16000
	v_mov_b32_e32 v141, 0
	global_load_lds_dwordx4 v132, s[8:9]
	v_readlane_b32 s8, v254, 45
	v_readlane_b32 s9, v254, 46
	s_add_u32 s28, s8, s5
	s_addc_u32 s29, s9, s4
	s_add_i32 s43, s42, 0x2000
	s_mov_b32 m0, s42
	s_add_u32 s4, s28, 0x18000
	global_load_lds_dwordx4 v138, s[28:29]
	s_mov_b32 m0, s43
	s_addc_u32 s5, s29, 0
	s_add_i32 s44, s42, 0x4000
	global_load_lds_dwordx4 v134, s[28:29]
	s_mov_b32 m0, s44
	s_add_i32 s45, s42, 0x6000
	global_load_lds_dwordx4 v138, s[4:5]
	s_mov_b32 m0, s45
	v_mov_b32_e32 v137, v141
	global_load_lds_dwordx4 v134, s[4:5]
	v_mov_b32_e32 v133, v141
	v_mov_b32_e32 v139, v141
	v_mov_b32_e32 v135, v141
	s_cmp_eq_u32 s1, 1
	v_lshl_add_u64 v[10:11], s[30:31], 0, v[136:137]
	v_lshl_add_u64 v[8:9], s[30:31], 0, v[132:133]
	v_lshl_add_u64 v[6:7], s[28:29], 0, v[138:139]
	v_lshl_add_u64 v[4:5], s[28:29], 0, v[134:135]
	s_cselect_b64 s[8:9], -1, 0
	s_cmp_lg_u32 s1, 1
	s_movk_i32 s46, 0x6000
	s_cbranch_scc1 .LBB0_641
	s_barrier
